# v24 + attn2: all 8 V-fragment LDS reads of the exp/PV section issued at its top into the (dead) K-fragment registers, counted lgkmcnt waits
# speedup vs baseline: 1.0011x; 1.0011x over previous
; #define MFMA32(a, b, c) __builtin_amdgcn_mfma_f32_32x32x16_bf16((a), (b), (c), 0, 0, 0)
; DI unsigned pk_bf16(float a, float b) { f32x2 v = {a, b}; bf2_t r = __builtin_convertvector(v, bf2_t); return __builtin_bit_cast(unsigned, r); }
;     ...
;             float ls = 0.f;
; #pragma unroll
;             for (int blk = 0; blk < 2; ++blk)
; #pragma unroll
;                 for (int i = 0; i < 16; ++i) { const float e = __builtin_amdgcn_exp2f(s[blk][i]); s[blk][i] = e; ls += e; }
;             l += ls;
;             }
; #pragma unroll
;             for (int blk = 0; blk < 2; ++blk)
; #pragma unroll
;                 for (int sp = 0; sp < 2; ++sp) {
;                     u32x4 pw;
;                     pw.x = pk_bf16(s[blk][8 * sp + 0], s[blk][8 * sp + 1]); pw.y = pk_bf16(s[blk][8 * sp + 2], s[blk][8 * sp + 3]);
;                     pw.z = pk_bf16(s[blk][8 * sp + 4], s[blk][8 * sp + 5]); pw.w = pk_bf16(s[blk][8 * sp + 6], s[blk][8 * sp + 7]);
;                     const bf16x8 pf = __builtin_bit_cast(bf16x8, pw);
; #pragma unroll
;                     for (int db = 0; db < DVB; ++db) {
;                         const unsigned char* va = sb + voff + db * 32 * 136 + (32 * blk + 16 * sp) * 2;
;                         const u32x2 lo = *(const u32x2*)va, hi = *(const u32x2*)(va + 16);
;                         u32x4 vw; vw.x = lo.x; vw.y = lo.y; vw.z = hi.x; vw.w = hi.y;
;                         o[db] = MFMA32(__builtin_bit_cast(bf16x8, vw), pf, o[db]);
;                     }
;                 }
.LBB0_3617:
	s_mul_hi_u32 s0, s49, 0xaaaaaaab
	s_lshr_b32 s0, s0, 1
	s_mul_i32 s0, s0, 0xd800
	v_subrev_u32_e32 v250, s0, v196
	v_add3_u32 v250, v199, s48, v250
	v_add_u32_e32 v251, 0x2000, v250
	v_add_u32_e32 v252, 0x3000, v250
	ds_read2_b64 v[212:215], v251 offset0:128 offset1:130
	ds_read2_b64 v[216:219], v252 offset0:160 offset1:162
	ds_read2_b64 v[220:223], v251 offset0:132 offset1:134
	ds_read2_b64 v[224:227], v252 offset0:164 offset1:166
	ds_read2_b64 v[228:231], v251 offset0:136 offset1:138
	ds_read2_b64 v[232:235], v252 offset0:168 offset1:170
	ds_read2_b64 v[236:239], v251 offset0:140 offset1:142
	ds_read2_b64 v[240:243], v252 offset0:172 offset1:174
	v_exp_f32_e32 v35, v1
	v_exp_f32_e32 v34, v2
	v_exp_f32_e32 v18, v18
	v_exp_f32_e32 v19, v19
	v_exp_f32_e32 v20, v20
	v_exp_f32_e32 v21, v21
	v_exp_f32_e32 v22, v22
	v_exp_f32_e32 v23, v23
	v_exp_f32_e32 v24, v24
	v_exp_f32_e32 v25, v25
	v_cvt_pk_bf16_f32 v40, v18, v19
	v_cvt_pk_bf16_f32 v41, v20, v21
	v_cvt_pk_bf16_f32 v42, v22, v23
	v_cvt_pk_bf16_f32 v43, v24, v25
	v_exp_f32_e32 v36, v4
	s_waitcnt lgkmcnt(7)
	v_mfma_f32_32x32x16_bf16 v[98:113], v[212:215], v[40:43], v[98:113]
	v_add_f32_e32 v4, 0, v18
	v_add_f32_e32 v4, v19, v4
	v_add_f32_e32 v4, v20, v4
	v_add_f32_e32 v4, v21, v4
	v_exp_f32_e32 v26, v26
	v_add_f32_e32 v4, v22, v4
	v_exp_f32_e32 v27, v27
	v_add_f32_e32 v4, v23, v4
	v_exp_f32_e32 v28, v28
	v_add_f32_e32 v4, v24, v4
	v_exp_f32_e32 v29, v29
	v_add_f32_e32 v4, v25, v4
	v_exp_f32_e32 v30, v30
	v_add_f32_e32 v4, v26, v4
	v_exp_f32_e32 v31, v31
	s_waitcnt lgkmcnt(6)
	v_mfma_f32_32x32x16_bf16 v[82:97], v[216:219], v[40:43], v[82:97]
	v_add_f32_e32 v4, v27, v4
	v_exp_f32_e32 v32, v32
	v_add_f32_e32 v4, v28, v4
	v_exp_f32_e32 v33, v33
	v_add_f32_e32 v4, v29, v4
	v_add_f32_e32 v4, v30, v4
	v_add_f32_e32 v4, v31, v4
	v_add_f32_e32 v4, v32, v4
	v_exp_f32_e32 v37, v17
	v_add_f32_e32 v4, v33, v4
	v_exp_f32_e32 v38, v16
	v_add_f32_e32 v4, v34, v4
	v_add_f32_e32 v4, v35, v4
	v_exp_f32_e32 v39, v5
	v_cvt_pk_bf16_f32 v44, v26, v27
	v_cvt_pk_bf16_f32 v45, v28, v29
	v_cvt_pk_bf16_f32 v46, v30, v31
	v_cvt_pk_bf16_f32 v47, v32, v33
	v_add_f32_e32 v4, v36, v4
	s_waitcnt lgkmcnt(5)
	v_mfma_f32_32x32x16_bf16 v[98:113], v[220:223], v[44:47], v[98:113]
	v_exp_f32_e32 v40, v6
	v_add_f32_e32 v4, v37, v4
	v_exp_f32_e32 v41, v7
	v_add_f32_e32 v4, v38, v4
	v_add_f32_e32 v4, v39, v4
	v_add_f32_e32 v4, v40, v4
	v_add_f32_e32 v16, v41, v4
	s_waitcnt lgkmcnt(4)
	v_mfma_f32_32x32x16_bf16 v[82:97], v[224:227], v[44:47], v[82:97]
	v_exp_f32_e32 v42, v8
	v_exp_f32_e32 v43, v9
	v_cvt_pk_bf16_f32 v114, v34, v35
	v_cvt_pk_bf16_f32 v115, v36, v37
	v_cvt_pk_bf16_f32 v116, v38, v39
	v_cvt_pk_bf16_f32 v117, v40, v41
	v_exp_f32_e32 v46, v12
	v_exp_f32_e32 v47, v13
	s_waitcnt lgkmcnt(3)
	v_mfma_f32_32x32x16_bf16 v[98:113], v[228:231], v[114:117], v[98:113]
	v_add_f32_e32 v4, v42, v16
	v_add_f32_e32 v16, v43, v4
	v_exp_f32_e32 v48, v14
	v_exp_f32_e32 v49, v15
	v_exp_f32_e32 v44, v10
	s_waitcnt lgkmcnt(2)
	v_mfma_f32_32x32x16_bf16 v[82:97], v[232:235], v[114:117], v[82:97]
	v_exp_f32_e32 v45, v11
	v_cvt_pk_bf16_f32 v8, v42, v43
	v_cvt_pk_bf16_f32 v10, v46, v47
	v_cvt_pk_bf16_f32 v11, v48, v49
	v_cvt_pk_bf16_f32 v9, v44, v45
	v_add_f32_e32 v1, v44, v16
	v_add_f32_e32 v1, v45, v1
	s_waitcnt lgkmcnt(1)
	v_mfma_f32_32x32x16_bf16 v[98:113], v[236:239], v[8:11], v[98:113]
	v_add_f32_e32 v1, v46, v1
	v_add_f32_e32 v1, v47, v1
	v_add_f32_e32 v1, v48, v1
	v_add_f32_e32 v1, v49, v1
	v_add_f32_e32 v173, v173, v1
	s_waitcnt lgkmcnt(0)
	v_mfma_f32_32x32x16_bf16 v[82:97], v[240:243], v[8:11], v[82:97]

; #define MFMA32(a, b, c) __builtin_amdgcn_mfma_f32_32x32x16_bf16((a), (b), (c), 0, 0, 0)
; DI unsigned pk_bf16(float a, float b) { f32x2 v = {a, b}; bf2_t r = __builtin_convertvector(v, bf2_t); return __builtin_bit_cast(unsigned, r); }
;     ...
;             float ls = 0.f;
; #pragma unroll
;             for (int blk = 0; blk < 2; ++blk)
; #pragma unroll
;                 for (int i = 0; i < 16; ++i) { const float e = __builtin_amdgcn_exp2f(s[blk][i]); s[blk][i] = e; ls += e; }
;             l += ls;
;             }
; #pragma unroll
;             for (int blk = 0; blk < 2; ++blk)
; #pragma unroll
;                 for (int sp = 0; sp < 2; ++sp) {
;                     u32x4 pw;
;                     pw.x = pk_bf16(s[blk][8 * sp + 0], s[blk][8 * sp + 1]); pw.y = pk_bf16(s[blk][8 * sp + 2], s[blk][8 * sp + 3]);
;                     pw.z = pk_bf16(s[blk][8 * sp + 4], s[blk][8 * sp + 5]); pw.w = pk_bf16(s[blk][8 * sp + 6], s[blk][8 * sp + 7]);
;                     const bf16x8 pf = __builtin_bit_cast(bf16x8, pw);
; #pragma unroll
;                     for (int db = 0; db < DVB; ++db) {
;                         const unsigned char* va = sb + voff + db * 32 * 136 + (32 * blk + 16 * sp) * 2;
;                         const u32x2 lo = *(const u32x2*)va, hi = *(const u32x2*)(va + 16);
;                         u32x4 vw; vw.x = lo.x; vw.y = lo.y; vw.z = hi.x; vw.w = hi.y;
;                         o[db] = MFMA32(__builtin_bit_cast(bf16x8, vw), pf, o[db]);
;                     }
;                 }
.LBB0_3635:
	v_subrev_u32_e32 v250, s51, v196
	v_add3_u32 v250, v199, s48, v250
	v_add_u32_e32 v251, 0x6800, v250
	v_add_u32_e32 v252, 0x7800, v250
	ds_read2_b64 v[212:215], v251 offset0:128 offset1:130
	ds_read2_b64 v[216:219], v252 offset0:160 offset1:162
	ds_read2_b64 v[220:223], v251 offset0:132 offset1:134
	ds_read2_b64 v[224:227], v252 offset0:164 offset1:166
	ds_read2_b64 v[228:231], v251 offset0:136 offset1:138
	ds_read2_b64 v[232:235], v252 offset0:168 offset1:170
	ds_read2_b64 v[236:239], v251 offset0:140 offset1:142
	ds_read2_b64 v[240:243], v252 offset0:172 offset1:174
	v_exp_f32_e32 v51, v1
	v_exp_f32_e32 v50, v2
	v_exp_f32_e32 v52, v4
	v_exp_f32_e32 v53, v17
	v_exp_f32_e32 v54, v16
	v_exp_f32_e32 v55, v55
	v_exp_f32_e32 v56, v56
	v_exp_f32_e32 v57, v57
	v_cvt_pk_bf16_f32 v72, v50, v51
	v_cvt_pk_bf16_f32 v73, v52, v53
	v_cvt_pk_bf16_f32 v74, v54, v55
	v_cvt_pk_bf16_f32 v75, v56, v57
	v_add_f32_e32 v4, 0, v50
	s_waitcnt lgkmcnt(7)
	v_mfma_f32_32x32x16_bf16 v[98:113], v[212:215], v[72:75], v[98:113]
	v_add_f32_e32 v4, v51, v4
	v_add_f32_e32 v4, v52, v4
	v_add_f32_e32 v4, v53, v4
	v_exp_f32_e32 v58, v58
	v_add_f32_e32 v4, v54, v4
	v_exp_f32_e32 v59, v59
	v_add_f32_e32 v4, v55, v4
	v_exp_f32_e32 v60, v60
	v_add_f32_e32 v4, v56, v4
	v_exp_f32_e32 v61, v61
	v_add_f32_e32 v4, v57, v4
	v_exp_f32_e32 v62, v62
	v_add_f32_e32 v4, v58, v4
	v_exp_f32_e32 v63, v63
	s_waitcnt lgkmcnt(6)
	v_mfma_f32_32x32x16_bf16 v[82:97], v[216:219], v[72:75], v[82:97]
	v_add_f32_e32 v4, v59, v4
	v_exp_f32_e32 v64, v64
	v_add_f32_e32 v4, v60, v4
	v_exp_f32_e32 v65, v65
	v_add_f32_e32 v4, v61, v4
	v_exp_f32_e32 v66, v66
	v_add_f32_e32 v4, v62, v4
	v_exp_f32_e32 v67, v67
	v_add_f32_e32 v4, v63, v4
	v_exp_f32_e32 v68, v68
	v_add_f32_e32 v4, v64, v4
	v_exp_f32_e32 v69, v69
	v_add_f32_e32 v4, v65, v4
	v_exp_f32_e32 v70, v70
	v_add_f32_e32 v4, v66, v4
	v_add_f32_e32 v4, v67, v4
	v_exp_f32_e32 v71, v5
	v_cvt_pk_bf16_f32 v76, v58, v59
	v_cvt_pk_bf16_f32 v77, v60, v61
	v_cvt_pk_bf16_f32 v78, v62, v63
	v_cvt_pk_bf16_f32 v79, v64, v65
	v_add_f32_e32 v4, v68, v4
	s_waitcnt lgkmcnt(5)
	v_mfma_f32_32x32x16_bf16 v[98:113], v[220:223], v[76:79], v[98:113]
	v_exp_f32_e32 v72, v6
	v_add_f32_e32 v4, v69, v4
	v_exp_f32_e32 v73, v7
	v_add_f32_e32 v4, v70, v4
	v_add_f32_e32 v4, v71, v4
	v_add_f32_e32 v4, v72, v4
	v_add_f32_e32 v16, v73, v4
	s_waitcnt lgkmcnt(4)
	v_mfma_f32_32x32x16_bf16 v[82:97], v[224:227], v[76:79], v[82:97]
	v_exp_f32_e32 v74, v8
	v_exp_f32_e32 v75, v9
	v_cvt_pk_bf16_f32 v116, v66, v67
	v_cvt_pk_bf16_f32 v117, v68, v69
	v_cvt_pk_bf16_f32 v118, v70, v71
	v_cvt_pk_bf16_f32 v119, v72, v73
	v_exp_f32_e32 v78, v12
	v_exp_f32_e32 v79, v13
	s_waitcnt lgkmcnt(3)
	v_mfma_f32_32x32x16_bf16 v[98:113], v[228:231], v[116:119], v[98:113]
	v_add_f32_e32 v4, v74, v16
	v_add_f32_e32 v16, v75, v4
	v_exp_f32_e32 v80, v14
	v_exp_f32_e32 v81, v15
	v_exp_f32_e32 v76, v10
	s_waitcnt lgkmcnt(2)
	v_mfma_f32_32x32x16_bf16 v[82:97], v[232:235], v[116:119], v[82:97]
	v_exp_f32_e32 v77, v11
	v_cvt_pk_bf16_f32 v8, v74, v75
	v_cvt_pk_bf16_f32 v10, v78, v79
	v_cvt_pk_bf16_f32 v11, v80, v81
	v_cvt_pk_bf16_f32 v9, v76, v77
	v_add_f32_e32 v1, v76, v16
	v_add_f32_e32 v1, v77, v1
	s_waitcnt lgkmcnt(1)
	v_mfma_f32_32x32x16_bf16 v[98:113], v[236:239], v[8:11], v[98:113]
	v_add_f32_e32 v1, v78, v1
	v_add_f32_e32 v1, v79, v1
	v_add_f32_e32 v1, v80, v1
	v_add_f32_e32 v1, v81, v1
	v_add_f32_e32 v173, v173, v1
	s_waitcnt lgkmcnt(0)
	v_mfma_f32_32x32x16_bf16 v[82:97], v[240:243], v[8:11], v[82:97]
